# one-barrier attention + first half-step: O rescale and scale/exp2 tail of partialSM placed before the K restage and the barrier (nothing but the V restage after the barrier)
# baseline (speedup 1.0000x reference)
.LBB0_651:
	v_cndmask_b32_e64 v1, v1, v196, s[40:41]
	v_sub_f32_e32 v88, v98, v1
	v_sub_f32_e32 v89, v99, v1
	v_sub_f32_e32 v90, v100, v1
	v_sub_f32_e32 v91, v101, v1
	v_sub_f32_e32 v92, v102, v1
	v_sub_f32_e32 v93, v103, v1
	v_sub_f32_e32 v94, v104, v1
	v_sub_f32_e32 v95, v105, v1
	v_sub_f32_e32 v78, v78, v1
	v_sub_f32_e32 v79, v79, v1
	v_sub_f32_e32 v96, v106, v1
	v_sub_f32_e32 v97, v107, v1
	v_sub_f32_e32 v74, v74, v1
	v_sub_f32_e32 v75, v75, v1
	v_sub_f32_e32 v80, v80, v1
	v_sub_f32_e32 v81, v81, v1
	v_exp_f32_e32 v196, v88
	v_exp_f32_e32 v203, v89
	v_exp_f32_e32 v112, v90
	v_exp_f32_e32 v202, v91
	v_exp_f32_e32 v110, v92
	v_exp_f32_e32 v113, v93
	v_exp_f32_e32 v109, v94
	v_exp_f32_e32 v111, v95
	v_exp_f32_e32 v103, v78
	v_exp_f32_e32 v107, v79
	v_exp_f32_e32 v101, v96
	v_exp_f32_e32 v106, v97
	v_exp_f32_e32 v99, v74
	v_exp_f32_e32 v102, v75
	v_exp_f32_e32 v98, v80
	v_exp_f32_e32 v100, v81
	s_add_i32 s0, s9, 1
	s_cmp_lt_i32 s0, s25
	s_cselect_b64 s[22:23], -1, 0
	s_cmp_ge_i32 s0, s25
	s_waitcnt vmcnt(1)
	ds_write_b128 v193, v[154:157] offset:32768
	s_waitcnt vmcnt(0)
	ds_write_b128 v193, v[158:161] offset:40960
	s_waitcnt lgkmcnt(0)
	s_barrier
	ds_write_b128 v194, v[146:149]
	ds_write_b128 v195, v[150:153]
	s_cbranch_scc1 .LBB0_653
	v_add_u32_e32 v80, 0x41, v218
	v_mad_i64_i32 v[74:75], s[0:1], v80, s33, v[164:165]
	v_add_u32_e32 v81, 0x61, v218
	v_mad_i64_i32 v[78:79], s[0:1], v81, s33, v[164:165]
	global_load_dwordx4 v[146:149], v[74:75], off
	global_load_dwordx4 v[150:153], v[78:79], off
	v_mad_i64_i32 v[74:75], s[0:1], v80, s33, v[166:167]
	v_mad_i64_i32 v[78:79], s[0:1], v81, s33, v[166:167]
	global_load_dwordx4 v[154:157], v[74:75], off
	global_load_dwordx4 v[158:161], v[78:79], off

.LBB0_829:
	v_cndmask_b32_e64 v132, v132, v168, s[40:41]
	v_mul_f32_e32 v183, 0xbe38aa3b, v132
	v_fmamk_f32 v82, v82, 0x3e38aa3b, v183
	v_fmamk_f32 v184, v66, 0x3e38aa3b, v183
	v_fmamk_f32 v66, v83, 0x3e38aa3b, v183
	v_fmamk_f32 v185, v67, 0x3e38aa3b, v183
	v_fmamk_f32 v67, v84, 0x3e38aa3b, v183
	v_fmamk_f32 v186, v68, 0x3e38aa3b, v183
	v_fmamk_f32 v68, v85, 0x3e38aa3b, v183
	v_fmamk_f32 v187, v69, 0x3e38aa3b, v183
	v_fmamk_f32 v69, v86, 0x3e38aa3b, v183
	v_fmamk_f32 v188, v70, 0x3e38aa3b, v183
	v_fmamk_f32 v70, v87, 0x3e38aa3b, v183
	v_fmamk_f32 v189, v71, 0x3e38aa3b, v183
	v_fmamk_f32 v71, v88, 0x3e38aa3b, v183
	v_fmamk_f32 v190, v72, 0x3e38aa3b, v183
	v_fmamk_f32 v72, v89, 0x3e38aa3b, v183
	v_fmamk_f32 v191, v73, 0x3e38aa3b, v183
	v_fmamk_f32 v73, v90, 0x3e38aa3b, v183
	v_fmamk_f32 v192, v74, 0x3e38aa3b, v183
	v_fmamk_f32 v74, v91, 0x3e38aa3b, v183
	v_fmamk_f32 v193, v75, 0x3e38aa3b, v183
	v_fmamk_f32 v75, v92, 0x3e38aa3b, v183
	v_fmamk_f32 v194, v76, 0x3e38aa3b, v183
	v_fmamk_f32 v76, v93, 0x3e38aa3b, v183
	v_fmamk_f32 v195, v77, 0x3e38aa3b, v183
	v_fmamk_f32 v77, v94, 0x3e38aa3b, v183
	v_fmamk_f32 v196, v78, 0x3e38aa3b, v183
	v_fmamk_f32 v78, v95, 0x3e38aa3b, v183
	v_fmamk_f32 v83, v96, 0x3e38aa3b, v183
	v_fmamk_f32 v84, v97, 0x3e38aa3b, v183
	v_exp_f32_e32 v146, v82
	v_exp_f32_e32 v168, v66
	v_exp_f32_e32 v144, v67
	v_exp_f32_e32 v147, v68
	v_exp_f32_e32 v142, v69
	v_exp_f32_e32 v145, v70
	v_exp_f32_e32 v141, v71
	v_exp_f32_e32 v143, v72
	v_exp_f32_e32 v138, v73
	v_exp_f32_e32 v140, v74
	v_exp_f32_e32 v136, v75
	v_exp_f32_e32 v139, v76
	v_exp_f32_e32 v134, v77
	v_exp_f32_e32 v137, v78
	v_exp_f32_e32 v133, v83
	v_exp_f32_e32 v135, v84
	s_add_i32 s0, s8, 1
	s_cmp_lt_i32 s0, s27
	v_fmamk_f32 v197, v79, 0x3e38aa3b, v183
	v_fmamk_f32 v198, v80, 0x3e38aa3b, v183
	v_fmac_f32_e32 v183, 0x3e38aa3b, v81
	s_cselect_b64 s[22:23], -1, 0
	s_cmp_ge_i32 s0, s27
	s_waitcnt vmcnt(2)
	ds_write_b128 v164, v[122:125] offset:32768
	s_waitcnt vmcnt(0)
	ds_write_b128 v164, v[126:129] offset:40960
	s_waitcnt lgkmcnt(0)
	s_barrier
	ds_write_b128 v165, v[114:117]
	ds_write_b128 v166, v[118:121]
	s_cbranch_scc1 .LBB0_831
	v_add_u32_e32 v66, 0x41, v182
	v_mad_i64_i32 v[66:67], s[0:1], v66, s33, v[130:131]
	v_add_u32_e32 v68, 0x61, v182
	v_mad_i64_i32 v[68:69], s[0:1], v68, s33, v[130:131]
	global_load_dwordx4 v[114:117], v[66:67], off offset:2048
	global_load_dwordx4 v[122:125], v[66:67], off offset:1024
	global_load_dwordx4 v[118:121], v[68:69], off offset:2048
	global_load_dwordx4 v[126:129], v[68:69], off offset:1024
